# P7 residual epilogue rewritten: 32 base loads software-pipelined 4 row-blocks ahead instead of one blocking load per store; plus K-loop DMA rebalance
# speedup vs baseline: 1.0120x; 1.0012x over previous
;     __device__ __forceinline__ void operator()(const f32x4 (&acc)[2][2][4][2], const Unit& u, int wr, int wc, int fr, int fq) const {
;         const int b = (u.pm * BM) >> 13; const float* gp = gate + (size_t)b * 12288;
;         const int col0 = u.pn * BM + wc * 32 + 4 * fq;
;         f32x4 gv[2][2];
; #pragma unroll
;         for (int bj = 0; bj < 2; ++bj)
; #pragma unroll
;             for (int n = 0; n < 2; ++n) gv[bj][n] = *(const f32x4*)(gp + col0 + bj * HALF + n * 16);
; #pragma unroll
;         for (int ai = 0; ai < 2; ++ai)
; #pragma unroll
;             for (int m = 0; m < 4; ++m) { const size_t off = (size_t)(u.pm * BM + ai * HALF + wr * 64 + m * 16 + fr) * 2048 + col0;
; #pragma unroll
;                 for (int bj = 0; bj < 2; ++bj)
; #pragma unroll
;                     for (int n = 0; n < 2; ++n) { const f32x4 bs = *(const f32x4*)(base + off + bj * HALF + n * 16);
;                         *(f32x4*)(out + off + bj * HALF + n * 16) = bs + gv[bj][n] * acc[ai][bj][m][n]; }
;                 if (m & 1) asm volatile("" ::: "memory"); }
;     }
.LBB0_944:
	v_lshl_add_u32 v160, s28, 8, v162
	s_ashr_i32 s21, s28, 5
	v_lshl_or_b32 v158, s48, 8, v164
	s_mul_hi_i32 s23, s21, 0xc000
	s_mul_i32 s21, s21, 0xc000
	v_ashrrev_i32_e32 v159, 31, v158
	s_add_u32 s30, s40, s21
	s_addc_u32 s31, s41, s23
	v_lshl_add_u64 v[130:131], v[158:159], 2, s[30:31]
	v_lshlrev_b32_e32 v172, 13, v160
	global_load_dwordx4 v[142:145], v[130:131], off
	global_load_dwordx4 v[138:141], v[130:131], off offset:64
	global_load_dwordx4 v[134:137], v[130:131], off offset:512
	v_lshl_add_u32 v172, v158, 2, v172
	global_load_dwordx4 v[130:133], v[130:131], off offset:576
	v_add_u32_e32 v173, 0x20000, v172
	v_add_u32_e32 v174, 0x40000, v172
	v_add_u32_e32 v175, 0x60000, v172
	v_add_u32_e32 v176, 0x100000, v172
	v_add_u32_e32 v177, 0x120000, v172
	v_add_u32_e32 v178, 0x140000, v172
	v_add_u32_e32 v179, 0x160000, v172
	global_load_dwordx4 v[188:191], v172, s[80:81]
	global_load_dwordx4 v[192:195], v172, s[80:81] offset:64
	global_load_dwordx4 v[196:199], v172, s[80:81] offset:512
	global_load_dwordx4 v[200:203], v172, s[80:81] offset:576
	global_load_dwordx4 v[204:207], v173, s[80:81]
	global_load_dwordx4 v[208:211], v173, s[80:81] offset:64
	global_load_dwordx4 v[212:215], v173, s[80:81] offset:512
	global_load_dwordx4 v[216:219], v173, s[80:81] offset:576
	global_load_dwordx4 v[220:223], v174, s[80:81]
	global_load_dwordx4 v[224:227], v174, s[80:81] offset:64
	global_load_dwordx4 v[228:231], v174, s[80:81] offset:512
	global_load_dwordx4 v[232:235], v174, s[80:81] offset:576
	global_load_dwordx4 v[236:239], v175, s[80:81]
	global_load_dwordx4 v[240:243], v175, s[80:81] offset:64
	global_load_dwordx4 v[244:247], v175, s[80:81] offset:512
	global_load_dwordx4 v[180:183], v175, s[80:81] offset:576
	s_andn2_b64 vcc, exec, s[0:1]
	s_mov_b64 s[0:1], -1
	s_waitcnt vmcnt(12)
	v_pk_fma_f32 v[126:127], v[126:127], v[142:143], v[188:189]
	v_pk_fma_f32 v[128:129], v[128:129], v[144:145], v[190:191]
	v_pk_fma_f32 v[122:123], v[122:123], v[138:139], v[192:193]
	v_pk_fma_f32 v[124:125], v[124:125], v[140:141], v[194:195]
	v_pk_fma_f32 v[118:119], v[118:119], v[134:135], v[196:197]
	v_pk_fma_f32 v[120:121], v[120:121], v[136:137], v[198:199]
	v_pk_fma_f32 v[106:107], v[106:107], v[130:131], v[200:201]
	v_pk_fma_f32 v[108:109], v[108:109], v[132:133], v[202:203]
	global_store_dwordx4 v172, v[126:129], s[12:13]
	global_store_dwordx4 v172, v[122:125], s[12:13] offset:64
	global_store_dwordx4 v172, v[118:121], s[12:13] offset:512
	global_store_dwordx4 v172, v[106:109], s[12:13] offset:576
	global_load_dwordx4 v[188:191], v176, s[80:81]
	global_load_dwordx4 v[192:195], v176, s[80:81] offset:64
	global_load_dwordx4 v[196:199], v176, s[80:81] offset:512
	global_load_dwordx4 v[200:203], v176, s[80:81] offset:576
	s_waitcnt vmcnt(16)
	v_pk_fma_f32 v[114:115], v[114:115], v[142:143], v[204:205]
	v_pk_fma_f32 v[116:117], v[116:117], v[144:145], v[206:207]
	v_pk_fma_f32 v[110:111], v[110:111], v[138:139], v[208:209]
	v_pk_fma_f32 v[112:113], v[112:113], v[140:141], v[210:211]
	v_pk_fma_f32 v[102:103], v[102:103], v[134:135], v[212:213]
	v_pk_fma_f32 v[104:105], v[104:105], v[136:137], v[214:215]
	v_pk_fma_f32 v[90:91], v[90:91], v[130:131], v[216:217]
	v_pk_fma_f32 v[92:93], v[92:93], v[132:133], v[218:219]
	global_store_dwordx4 v173, v[114:117], s[12:13]
	global_store_dwordx4 v173, v[110:113], s[12:13] offset:64
	global_store_dwordx4 v173, v[102:105], s[12:13] offset:512
	global_store_dwordx4 v173, v[90:93], s[12:13] offset:576
	global_load_dwordx4 v[204:207], v177, s[80:81]
	global_load_dwordx4 v[208:211], v177, s[80:81] offset:64
	global_load_dwordx4 v[212:215], v177, s[80:81] offset:512
	global_load_dwordx4 v[216:219], v177, s[80:81] offset:576
	s_waitcnt vmcnt(20)
	v_pk_fma_f32 v[98:99], v[98:99], v[142:143], v[220:221]
	v_pk_fma_f32 v[100:101], v[100:101], v[144:145], v[222:223]
	v_pk_fma_f32 v[94:95], v[94:95], v[138:139], v[224:225]
	v_pk_fma_f32 v[96:97], v[96:97], v[140:141], v[226:227]
	v_pk_fma_f32 v[86:87], v[86:87], v[134:135], v[228:229]
	v_pk_fma_f32 v[88:89], v[88:89], v[136:137], v[230:231]
	v_pk_fma_f32 v[74:75], v[74:75], v[130:131], v[232:233]
	v_pk_fma_f32 v[76:77], v[76:77], v[132:133], v[234:235]
	global_store_dwordx4 v174, v[98:101], s[12:13]
	global_store_dwordx4 v174, v[94:97], s[12:13] offset:64
	global_store_dwordx4 v174, v[86:89], s[12:13] offset:512
	global_store_dwordx4 v174, v[74:77], s[12:13] offset:576
	global_load_dwordx4 v[220:223], v178, s[80:81]
	global_load_dwordx4 v[224:227], v178, s[80:81] offset:64
	global_load_dwordx4 v[228:231], v178, s[80:81] offset:512
	global_load_dwordx4 v[232:235], v178, s[80:81] offset:576
	s_waitcnt vmcnt(24)
;     __device__ __forceinline__ void operator()(const f32x4 (&acc)[2][2][4][2], const Unit& u, int wr, int wc, int fr, int fq) const {
;     ...
; #pragma unroll
;         for (int ai = 0; ai < 2; ++ai)
; #pragma unroll
;             for (int m = 0; m < 4; ++m) { const size_t off = (size_t)(u.pm * BM + ai * HALF + wr * 64 + m * 16 + fr) * 2048 + col0;
; #pragma unroll
;                 for (int bj = 0; bj < 2; ++bj)
; #pragma unroll
;                     for (int n = 0; n < 2; ++n) { const f32x4 bs = *(const f32x4*)(base + off + bj * HALF + n * 16);
;                         *(f32x4*)(out + off + bj * HALF + n * 16) = bs + gv[bj][n] * acc[ai][bj][m][n]; }
;                 if (m & 1) asm volatile("" ::: "memory"); }
	v_pk_fma_f32 v[82:83], v[82:83], v[142:143], v[236:237]
	v_pk_fma_f32 v[84:85], v[84:85], v[144:145], v[238:239]
	v_pk_fma_f32 v[78:79], v[78:79], v[138:139], v[240:241]
	v_pk_fma_f32 v[80:81], v[80:81], v[140:141], v[242:243]
	v_pk_fma_f32 v[70:71], v[70:71], v[134:135], v[244:245]
	v_pk_fma_f32 v[72:73], v[72:73], v[136:137], v[246:247]
	v_pk_fma_f32 v[66:67], v[66:67], v[130:131], v[180:181]
	v_pk_fma_f32 v[68:69], v[68:69], v[132:133], v[182:183]
	global_store_dwordx4 v175, v[82:85], s[12:13]
	global_store_dwordx4 v175, v[78:81], s[12:13] offset:64
	global_store_dwordx4 v175, v[70:73], s[12:13] offset:512
	global_store_dwordx4 v175, v[66:69], s[12:13] offset:576
	global_load_dwordx4 v[236:239], v179, s[80:81]
	global_load_dwordx4 v[240:243], v179, s[80:81] offset:64
	global_load_dwordx4 v[244:247], v179, s[80:81] offset:512
	global_load_dwordx4 v[180:183], v179, s[80:81] offset:576
	s_waitcnt vmcnt(24)
	v_pk_fma_f32 v[62:63], v[62:63], v[142:143], v[188:189]
	v_pk_fma_f32 v[64:65], v[64:65], v[144:145], v[190:191]
	v_pk_fma_f32 v[58:59], v[58:59], v[138:139], v[192:193]
	v_pk_fma_f32 v[60:61], v[60:61], v[140:141], v[194:195]
	v_pk_fma_f32 v[54:55], v[54:55], v[134:135], v[196:197]
	v_pk_fma_f32 v[56:57], v[56:57], v[136:137], v[198:199]
	v_pk_fma_f32 v[42:43], v[42:43], v[130:131], v[200:201]
	v_pk_fma_f32 v[44:45], v[44:45], v[132:133], v[202:203]
	global_store_dwordx4 v176, v[62:65], s[12:13]
	global_store_dwordx4 v176, v[58:61], s[12:13] offset:64
	global_store_dwordx4 v176, v[54:57], s[12:13] offset:512
	global_store_dwordx4 v176, v[42:45], s[12:13] offset:576
	s_waitcnt vmcnt(20)
	v_pk_fma_f32 v[50:51], v[50:51], v[142:143], v[204:205]
	v_pk_fma_f32 v[52:53], v[52:53], v[144:145], v[206:207]
	v_pk_fma_f32 v[46:47], v[46:47], v[138:139], v[208:209]
	v_pk_fma_f32 v[48:49], v[48:49], v[140:141], v[210:211]
	v_pk_fma_f32 v[38:39], v[38:39], v[134:135], v[212:213]
	v_pk_fma_f32 v[40:41], v[40:41], v[136:137], v[214:215]
	v_pk_fma_f32 v[26:27], v[26:27], v[130:131], v[216:217]
	v_pk_fma_f32 v[28:29], v[28:29], v[132:133], v[218:219]
	global_store_dwordx4 v177, v[50:53], s[12:13]
	global_store_dwordx4 v177, v[46:49], s[12:13] offset:64
	global_store_dwordx4 v177, v[38:41], s[12:13] offset:512
	global_store_dwordx4 v177, v[26:29], s[12:13] offset:576
	s_waitcnt vmcnt(16)
	v_pk_fma_f32 v[34:35], v[34:35], v[142:143], v[220:221]
	v_pk_fma_f32 v[36:37], v[36:37], v[144:145], v[222:223]
	v_pk_fma_f32 v[30:31], v[30:31], v[138:139], v[224:225]
	v_pk_fma_f32 v[32:33], v[32:33], v[140:141], v[226:227]
	v_pk_fma_f32 v[22:23], v[22:23], v[134:135], v[228:229]
	v_pk_fma_f32 v[24:25], v[24:25], v[136:137], v[230:231]
	v_pk_fma_f32 v[10:11], v[10:11], v[130:131], v[232:233]
	v_pk_fma_f32 v[12:13], v[12:13], v[132:133], v[234:235]
	global_store_dwordx4 v178, v[34:37], s[12:13]
	global_store_dwordx4 v178, v[30:33], s[12:13] offset:64
	global_store_dwordx4 v178, v[22:25], s[12:13] offset:512
	global_store_dwordx4 v178, v[10:13], s[12:13] offset:576
	s_waitcnt vmcnt(12)
	v_pk_fma_f32 v[18:19], v[18:19], v[142:143], v[236:237]
	v_pk_fma_f32 v[20:21], v[20:21], v[144:145], v[238:239]
	v_pk_fma_f32 v[14:15], v[14:15], v[138:139], v[240:241]
	v_pk_fma_f32 v[16:17], v[16:17], v[140:141], v[242:243]
	v_pk_fma_f32 v[6:7], v[6:7], v[134:135], v[244:245]
	v_pk_fma_f32 v[8:9], v[8:9], v[136:137], v[246:247]
	v_pk_fma_f32 v[2:3], v[2:3], v[130:131], v[180:181]
	v_pk_fma_f32 v[4:5], v[4:5], v[132:133], v[182:183]
	global_store_dwordx4 v179, v[18:21], s[12:13]
	global_store_dwordx4 v179, v[14:17], s[12:13] offset:64
	global_store_dwordx4 v179, v[6:9], s[12:13] offset:512
	global_store_dwordx4 v179, v[2:5], s[12:13] offset:576
	s_cbranch_vccnz .LBB0_933
	s_andn2_b64 vcc, exec, s[6:7]
	s_cbranch_vccnz .LBB0_932
	s_barrier
	s_branch .LBB0_932
